# MLA loop: static s_setprio 1 for waves 0-3 instead of waves 4-7
# baseline (speedup 1.0000x reference)
; #define MLA_DMA(t, slot) do { _Pragma("unroll") for (int i_ = 0; i_ < 4; ++i_) { const bf16_t* src_ = (pisk[i_] ? kbase : vbase) + poff[i_] + (size_t)(t) * pstep[i_]; \
;         __builtin_amdgcn_global_load_lds((const unsigned*)src_, (LAS unsigned*)(lds + (slot) * SLOT + (w + 8 * i_) * 1024), 16, 0, 0); } } while (0)
; DI void mla_attn_phase(LAS unsigned char* lds, const bf16_t* Qg, const bf16_t* Kg, const bf16_t* Vtg, bf16_t* MIX) {
;     ...
;             const int qb = half ? pi : 63 - pi, q0 = qb * 256 + 32 * w, NT = 4 * (qb + 1);
;     ...
;             const bf16_t* qp = Qg + ((size_t)bh * SEQ + q0 + r32) * 96 + 8 * hf;
;             bf16x8 qf[6];
; #pragma unroll
;             for (int ks = 0; ks < 6; ++ks) qf[ks] = *(const bf16x8*)(qp + 16 * ks);
;             asm volatile("" ::: "memory");
;             MLA_DMA(0, 0); MLA_DMA(1, 1);
;             f32x16 o[4];
; #pragma unroll
;             for (int mt = 0; mt < 4; ++mt)
; #pragma unroll
;                 for (int i = 0; i < 16; ++i) o[mt][i] = 0.f;
;             float m_run = -1e30f, l_run = 0.f;
;     ...
;             asm volatile("s_waitcnt vmcnt(4)" ::: "memory");
;             __builtin_amdgcn_s_barrier(); asm volatile("" ::: "memory");
;             int sl = 0;
.LBB0_357:
	s_and_b64 s[26:27], s[24:25], exec
	s_cselect_b32 s8, s37, s36
	s_lshl_b32 s26, s8, 8
	s_add_i32 s26, s26, s34
	s_ashr_i32 s27, s26, 31
	v_lshl_add_u64 v[0:1], v[180:181], 0, s[26:27]
	s_movk_i32 s30, 0xc0
	s_waitcnt lgkmcnt(0)
	v_mad_u64_u32 v[4:5], s[28:29], v0, s30, v[168:169]
	v_mad_i32_i24 v5, v1, s30, v5
	s_mov_b32 m0, s35
	global_load_dwordx4 v[112:115], v[4:5], off
	global_load_dwordx4 v[116:119], v[4:5], off offset:32
	global_load_dwordx4 v[120:123], v[4:5], off offset:64
	global_load_dwordx4 v[124:127], v[4:5], off offset:96
	global_load_dwordx4 v[128:131], v[4:5], off offset:128
	global_load_dwordx4 v[132:135], v[4:5], off offset:160
	global_load_lds_dwordx4 v[184:185], off
	s_add_i32 m0, s35, 0x2000
	s_nop 0
	global_load_lds_dwordx4 v[186:187], off
	s_add_i32 m0, s35, 0x4000
	s_nop 0
	global_load_lds_dwordx4 v[188:189], off
	s_add_i32 m0, s35, 0x6000
	s_nop 0
	global_load_lds_dwordx4 v[190:191], off
	s_add_i32 m0, s35, 0x8000
	s_nop 0
	global_load_lds_dwordx4 v[192:193], off
	s_add_i32 m0, s35, 0xa000
	s_nop 0
	global_load_lds_dwordx4 v[194:195], off
	s_add_i32 m0, s35, 0xc000
	s_nop 0
	global_load_lds_dwordx4 v[196:197], off
	s_add_i32 m0, s35, 0xe000
	s_cmp_lt_i32 s8, 0
	global_load_lds_dwordx4 v[198:199], off
	s_waitcnt vmcnt(4)
	s_barrier
	s_cbranch_scc1 .LBB0_355
	s_waitcnt lgkmcnt(0)
	v_mov_b32_e32 v14, v2
	v_mov_b32_e32 v15, v2
	s_lshl_b32 s8, s8, 2
	v_mov_b32_e32 v0, v2
	v_mov_b32_e32 v1, v2
	v_mov_b32_e32 v3, v2
	v_mov_b32_e32 v4, v2
	v_mov_b32_e32 v5, v2
	v_mov_b32_e32 v6, v2
	v_mov_b32_e32 v7, v2
	v_mov_b32_e32 v8, v2
	v_mov_b32_e32 v9, v2
	v_mov_b32_e32 v10, v2
	v_mov_b32_e32 v11, v2
	v_mov_b32_e32 v12, v2
	v_mov_b32_e32 v13, v2
	v_mov_b64_e32 v[30:31], v[14:15]
	v_mov_b64_e32 v[46:47], v[14:15]
	v_mov_b64_e32 v[62:63], v[14:15]
	v_mov_b64_e32 v[78:79], v[14:15]
	s_add_i32 s38, s8, 4
	s_or_b32 s39, s26, 31
	v_or_b32_e32 v167, s26, v164
	s_mov_b32 s40, 0
	v_mov_b32_e32 v234, 0xf149f2ca
	v_mov_b32_e32 v233, 0
	v_mov_b64_e32 v[210:211], v[208:209]
	v_mov_b64_e32 v[212:213], v[206:207]
	v_mov_b64_e32 v[214:215], v[204:205]
	v_mov_b64_e32 v[216:217], v[202:203]
	v_mov_b64_e32 v[28:29], v[12:13]
	v_mov_b64_e32 v[26:27], v[10:11]
	v_mov_b64_e32 v[24:25], v[8:9]
	v_mov_b64_e32 v[22:23], v[6:7]
	v_mov_b64_e32 v[20:21], v[4:5]
	v_mov_b64_e32 v[18:19], v[2:3]
	v_mov_b64_e32 v[16:17], v[0:1]
	v_mov_b64_e32 v[44:45], v[12:13]
	v_mov_b64_e32 v[42:43], v[10:11]
	v_mov_b64_e32 v[40:41], v[8:9]
	v_mov_b64_e32 v[38:39], v[6:7]
	v_mov_b64_e32 v[36:37], v[4:5]
	v_mov_b64_e32 v[34:35], v[2:3]
	v_mov_b64_e32 v[32:33], v[0:1]
	v_mov_b64_e32 v[60:61], v[12:13]
	v_mov_b64_e32 v[58:59], v[10:11]
	v_mov_b64_e32 v[56:57], v[8:9]
	v_mov_b64_e32 v[54:55], v[6:7]
	v_mov_b64_e32 v[52:53], v[4:5]
	v_mov_b64_e32 v[50:51], v[2:3]
	v_mov_b64_e32 v[48:49], v[0:1]
	v_mov_b64_e32 v[76:77], v[12:13]
	v_mov_b64_e32 v[74:75], v[10:11]
	v_mov_b64_e32 v[72:73], v[8:9]
	v_mov_b64_e32 v[70:71], v[6:7]
	v_mov_b64_e32 v[68:69], v[4:5]
	v_mov_b64_e32 v[66:67], v[2:3]
	v_mov_b64_e32 v[64:65], v[0:1]
	s_mov_b32 s41, 0
	s_mov_b32 s42, 0
	s_waitcnt vmcnt(0)
	s_setprio 1
	s_cmp_lt_u32 s34, 0x80
	s_cbranch_scc1 .Lmla_pro_done
	s_add_i32 s31, s35, 0x10000
	s_mov_b32 m0, s31
	s_nop 0
	global_load_lds_dwordx4 v[210:211], off
	s_add_i32 m0, s31, 0x2000
	s_nop 0
	global_load_lds_dwordx4 v[212:213], off
	s_add_i32 m0, s31, 0x4000
	s_nop 0
	global_load_lds_dwordx4 v[214:215], off
	s_add_i32 m0, s31, 0x6000
	s_nop 0
	global_load_lds_dwordx4 v[216:217], off
	v_lshl_add_u64 v[216:217], v[216:217], 0, s[18:19]
	v_lshl_add_u64 v[214:215], v[214:215], 0, s[20:21]
	v_lshl_add_u64 v[212:213], v[212:213], 0, s[2:3]
	v_lshl_add_u64 v[210:211], v[210:211], 0, s[22:23]
	s_setprio 0
	s_barrier
